# neighbourhood attention: bias gathers issued at the loop top ahead of the K/V prefetch loads, counted wait (vmcnt 2) at their use
# speedup vs baseline: 1.0054x; 1.0018x over previous
.LBB0_655:
	s_cmp_gt_u32 s48, 3
	s_cbranch_scc0 .Lna_pre_done
	s_add_i32 s100, s52, s48
	v_cmp_ge_i32_e32 vcc, s100, v99
	v_cmp_lt_i32_e64 s[98:99], s100, v100
	s_mov_b64 s[96:97], exec
	s_and_b64 s[98:99], vcc, s[98:99]
	s_and_b64 s[98:99], s[98:99], s[96:97]
	v_mov_b32_e32 v134, v94
	v_ashrrev_i32_e32 v135, 31, v94
	s_and_b64 exec, s[98:99], s[14:15]
	s_cbranch_execz .Lna_p0
	v_lshl_add_u64 v[136:137], v[134:135], 0, v[78:79]
	v_lshl_add_u64 v[136:137], v[136:137], 2, s[12:13]
	global_load_dword v126, v[136:137], off offset:868
.Lna_p0:
	s_and_b64 exec, s[98:99], s[22:23]
	s_cbranch_execz .Lna_p1
	v_lshl_add_u64 v[136:137], v[134:135], 0, v[76:77]
	v_lshl_add_u64 v[136:137], v[136:137], 2, s[12:13]
	global_load_dword v127, v[136:137], off offset:868
.Lna_p1:
	s_and_b64 exec, s[98:99], s[24:25]
	s_cbranch_execz .Lna_p2
	v_lshl_add_u64 v[136:137], v[134:135], 0, v[82:83]
	v_lshl_add_u64 v[136:137], v[136:137], 2, s[12:13]
	global_load_dword v128, v[136:137], off offset:868
.Lna_p2:
	s_and_b64 exec, s[98:99], s[26:27]
	s_cbranch_execz .Lna_p3
	v_lshl_add_u64 v[136:137], v[134:135], 0, v[80:81]
	v_lshl_add_u64 v[136:137], v[136:137], 2, s[12:13]
	global_load_dword v129, v[136:137], off offset:868
.Lna_p3:
	s_and_b64 exec, s[98:99], s[28:29]
	s_cbranch_execz .Lna_p4
	v_lshl_add_u64 v[136:137], v[134:135], 0, v[86:87]
	v_lshl_add_u64 v[136:137], v[136:137], 2, s[12:13]
	global_load_dword v130, v[136:137], off offset:868
.Lna_p4:
	s_and_b64 exec, s[98:99], s[30:31]
	s_cbranch_execz .Lna_p5
	v_lshl_add_u64 v[136:137], v[134:135], 0, v[84:85]
	v_lshl_add_u64 v[136:137], v[136:137], 2, s[12:13]
	global_load_dword v131, v[136:137], off offset:868
.Lna_p5:
	s_and_b64 exec, s[98:99], s[42:43]
	s_cbranch_execz .Lna_p6
	v_lshl_add_u64 v[136:137], v[134:135], 0, v[90:91]
	v_lshl_add_u64 v[136:137], v[136:137], 2, s[12:13]
	global_load_dword v132, v[136:137], off offset:868
.Lna_p6:
	s_and_b64 exec, s[98:99], s[44:45]
	s_cbranch_execz .Lna_p7
	v_lshl_add_u64 v[136:137], v[134:135], 0, v[88:89]
	v_lshl_add_u64 v[136:137], v[136:137], 2, s[12:13]
	global_load_dword v133, v[136:137], off offset:868
.Lna_p7:
	s_mov_b64 exec, s[96:97]

.LBB0_658:
	v_lshl_add_u64 v[2:3], s[40:41], 0, v[72:73]
	v_mad_u64_u32 v[4:5], s[56:57], v2, s2, v[92:93]
	v_mad_i32_i24 v5, v3, s2, v5
	v_lshl_add_u64 v[2:3], s[40:41], 1, v[74:75]
	s_waitcnt vmcnt(8)
	global_load_dwordx4 v[28:31], v[4:5], off
	global_load_dwordx4 v[32:35], v[2:3], off
.LBB0_659:
	s_bitcmp1_b32 s48, 0
	s_cselect_b32 s40, 0x4800, 0
	s_add_i32 s56, s40, 16
	s_cmp_gt_u32 s48, 3
	s_mov_b64 s[40:41], -1
	s_cbranch_scc0 .LBB0_685
	s_add_i32 s40, s52, s48
	v_cmp_ge_i32_e32 vcc, s40, v99
	v_cmp_lt_i32_e64 s[40:41], s40, v100
	v_mov_b64_e32 v[16:17], v[36:37]
	v_mov_b64_e32 v[4:5], v[40:41]
	v_mov_b64_e32 v[8:9], v[44:45]
	v_mov_b64_e32 v[12:13], v[48:49]
	s_and_b64 s[48:49], vcc, s[40:41]
	v_mov_b32_e32 v56, v109
	v_mov_b32_e32 v95, v110
	v_mov_b64_e32 v[18:19], v[38:39]
	v_mov_b64_e32 v[6:7], v[42:43]
	v_mov_b64_e32 v[10:11], v[46:47]
	v_mov_b64_e32 v[14:15], v[50:51]
	s_and_saveexec_b64 s[40:41], s[48:49]
	s_cbranch_execz .LBB0_680
	v_ashrrev_i32_e32 v95, 31, v94
	v_mov_b32_e32 v14, 0xff800000
	v_mov_b32_e32 v0, 0xff800000
	v_mov_b32_e32 v15, 0xff800000
	v_mov_b32_e32 v112, 0xff800000
	v_mov_b32_e32 v111, 0xff800000
	v_mov_b32_e32 v113, 0xff800000
	v_mov_b32_e32 v114, 0xff800000
	v_mov_b32_e32 v115, 0xff800000
	s_cmp_lg_u64 s[46:47], 0
	s_cbranch_scc0 .Lna_w0
	s_waitcnt vmcnt(2) lgkmcnt(0)
	s_branch .Lna_w1

.Lna_w1:
	v_mul_f32_e32 v126, 0x3fb8aa3b, v126
	v_cndmask_b32_e64 v0, v0, v126, s[14:15]
	v_mul_f32_e32 v127, 0x3fb8aa3b, v127
	v_cndmask_b32_e64 v14, v14, v127, s[22:23]
	v_mul_f32_e32 v128, 0x3fb8aa3b, v128
	v_cndmask_b32_e64 v112, v112, v128, s[24:25]
	v_mul_f32_e32 v129, 0x3fb8aa3b, v129
	v_cndmask_b32_e64 v15, v15, v129, s[26:27]
	v_mul_f32_e32 v130, 0x3fb8aa3b, v130
	v_cndmask_b32_e64 v113, v113, v130, s[28:29]
	v_mul_f32_e32 v131, 0x3fb8aa3b, v131
	v_cndmask_b32_e64 v111, v111, v131, s[30:31]
	v_mul_f32_e32 v132, 0x3fb8aa3b, v132
	v_cndmask_b32_e64 v115, v115, v132, s[42:43]
	v_mul_f32_e32 v133, 0x3fb8aa3b, v133
	v_cndmask_b32_e64 v114, v114, v133, s[44:45]
